# diff-attention tile loop: waves 4-7 sleep 384 cycles after each tile barrier so the two waves of a SIMD run their MFMA and softmax segments out of phase (stacked on v21)
# baseline (speedup 1.0000x reference)
.LBB0_270:
	s_and_b64 vcc, exec, s[38:39]
	s_waitcnt lgkmcnt(0)
	s_barrier
	v_readfirstlane_b32 s99, v196
	s_lshr_b32 s99, s99, 8
	s_cbranch_scc0 .Lws_m00
	s_sleep 6
.Lws_m00:
	s_cbranch_vccz .LBB0_272
	s_mov_b64 s[12:13], s[10:11]
	s_cbranch_execz .LBB0_273
	s_branch .LBB0_274

; template <int MODE> ...
;     ...
;     ATT_LOAD(ATT_TILE(0), kstA, vstA, lfA); ATT_WRITE(ATT_TILE(0), 0, kstA, vstA, lfA);
;     if (nt > 1) ATT_LOAD(ATT_TILE(1), kstB, vstB, lfB);
;     __syncthreads();
;     bool stop = false;
;     for (int it = 0; it < nt; it += 2) {
;         ATT_STEP(it, kstA, vstA, lfA, kstB, vstB, lfB);
;         if (stop || it + 1 >= nt) break;
;         ATT_STEP(it + 1, kstB, vstB, lfB, kstA, vstA, lfA);
.Lws_m01:
	s_cbranch_vccz .LBB0_299
	s_mov_b64 s[10:11], s[8:9]
	s_cbranch_execz .LBB0_300
	s_branch .LBB0_301
